# FFN-up epilogue packed gelu: the two pairs of each half interleaved step by step (dependent packed ops no longer back to back)
# speedup vs baseline: 1.0054x; 1.0054x over previous
;     __device__ __forceinline__ void operator()(const f32x4 (&acc)[2][2][4][2], const Unit& u, int wr, int wc, int fr, int fq) const {
;     ...
;                 bool valid; int grow; bool zp = false, zn = false;
;                 if (!fix) { valid = !((ai == 0 && m == 0 && fr == 0) || (ai == 1 && m == 3 && fr == 15)); grow = u.pm * BM + wr * HALF + ai * 64 + m * 16 + fr; }
;                 else { const int R = (u.pm - nmain) * BM + wr * HALF + ai * 64 + m * 16 + fr; const int grp = R >> 2, pos = R & 3;
;                     const bool ss = (grp < 256) ? ((grp & 15) == 0) : (grp == 256);
;                     valid = (pos == 1) || (pos == 2); grow = (pos == 1) ? ((grp * 128 - 1 + mrows) % mrows) : (grp * 128);
;                     zn = (pos == 1) && ss; zp = (pos == 2) && ss; }
;                 f32x4 res[2];
;                 const float fzp = zp ? 0.f : 1.f, fzn = zn ? 0.f : 1.f;
; #pragma unroll
;                 for (int n = 0; n < 2; ++n) {
;                     const f32x4 g = acc[ai][0][m][n], up = acc[ai][1][m][n];
;                     f32x4 tp = g, tn = g;
;                     if (!fix) { const f32x4 gm = (m > 0) ? acc[ai][0][m - 1][n] : acc[ai ^ 1][0][3][n], gx = (m < 3) ? acc[ai][0][m + 1][n] : acc[ai ^ 1][0][0][n];
;                         tp = (fr == 15) ? gm : g; tn = (fr == 0) ? gx : g; }
;                     f32x4 gp, gn;
; #pragma unroll
;                     for (int j = 0; j < 4; ++j) { gp[j] = dpp_ror1(tp[j]); gn[j] = dpp_ror15(tn[j]); }
;                     const f32x4 cv = (w0[n] * fzp) * gp + (w1[n] * g + ((w2[n] * fzn) * gn + bb[n]));
;                     const f32x4 inner = cv * (cv * cv * 0.044715f + 1.0f) * (-2.0f * 0.7978845608028654f * 1.4426950408889634f);
;                     f32x4 sg;
; #pragma unroll
;                     for (int j = 0; j < 4; ++j) sg[j] = __builtin_amdgcn_rcpf(1.0f + __builtin_amdgcn_exp2f(inner[j]));
;                     res[n] = cv * sg * up;
;                 }
;                 if (valid) { u32x4 w; w.x = cvt_pk_bf16(res[0][0], res[0][1]); w.y = cvt_pk_bf16(res[0][2], res[0][3]); w.z = cvt_pk_bf16(res[1][0], res[1][1]); w.w = cvt_pk_bf16(res[1][2], res[1][3]);
;                     __builtin_nontemporal_store(w, (u32x4*)(ACT + (size_t)grow * 4096 + ch0)); }
.LBB0_631:
	s_and_b64 s[16:17], s[0:1], s[18:19]
	s_and_b64 s[18:19], s[4:5], s[18:19]
	v_cndmask_b32_e64 v188, v36, v140, s[18:19]
	v_cndmask_b32_e64 v184, v36, v12, s[16:17]
	v_cndmask_b32_e64 v185, v39, v143, s[18:19]
	v_cndmask_b32_e64 v186, v38, v142, s[18:19]
	v_cndmask_b32_e64 v187, v37, v141, s[18:19]
	v_mov_b32_dpp v196, v188 row_ror:15 row_mask:0xf bank_mask:0xf
	v_cndmask_b32_e64 v189, v28, v136, s[18:19]
	v_cndmask_b32_e64 v179, v39, v15, s[16:17]
	v_cndmask_b32_e64 v181, v38, v14, s[16:17]
	v_cndmask_b32_e64 v183, v37, v13, s[16:17]
	v_mov_b32_dpp v192, v184 row_ror:1 row_mask:0xf bank_mask:0xf
	v_mov_b32_dpp v197, v187 row_ror:15 row_mask:0xf bank_mask:0xf
	v_mov_b32_dpp v198, v186 row_ror:15 row_mask:0xf bank_mask:0xf
	v_mov_b32_dpp v199, v185 row_ror:15 row_mask:0xf bank_mask:0xf
	v_cndmask_b32_e64 v185, v28, v8, s[16:17]
	v_cndmask_b32_e64 v187, v30, v138, s[18:19]
	v_cndmask_b32_e64 v186, v29, v137, s[18:19]
	v_mov_b32_dpp v188, v189 row_ror:15 row_mask:0xf bank_mask:0xf
	v_mov_b32_dpp v193, v183 row_ror:1 row_mask:0xf bank_mask:0xf
	v_mov_b32_dpp v194, v181 row_ror:1 row_mask:0xf bank_mask:0xf
	v_mov_b32_dpp v195, v179 row_ror:1 row_mask:0xf bank_mask:0xf
	v_cndmask_b32_e64 v179, v31, v11, s[16:17]
	v_cndmask_b32_e64 v181, v30, v10, s[16:17]
	v_cndmask_b32_e64 v183, v29, v9, s[16:17]
	v_cndmask_b32_e64 v212, v31, v139, s[18:19]
	v_mov_b32_dpp v184, v185 row_ror:1 row_mask:0xf bank_mask:0xf
	v_mov_b32_dpp v189, v186 row_ror:15 row_mask:0xf bank_mask:0xf
	v_mov_b32_dpp v190, v187 row_ror:15 row_mask:0xf bank_mask:0xf
	v_mov_b32_dpp v185, v183 row_ror:1 row_mask:0xf bank_mask:0xf
	v_mov_b32_dpp v186, v181 row_ror:1 row_mask:0xf bank_mask:0xf
	v_mov_b32_dpp v187, v179 row_ror:1 row_mask:0xf bank_mask:0xf
	v_mov_b32_dpp v191, v212 row_ror:15 row_mask:0xf bank_mask:0xf
	s_waitcnt lgkmcnt(0)
	s_and_saveexec_b64 s[20:21], s[82:83]
	s_cbranch_execz .LBB0_633
	v_pk_mul_f32 v[218:219], v[96:97], v[180:181] op_sel_hi:[1,0]
	v_pk_mul_f32 v[214:215], v[88:89], v[182:183] op_sel_hi:[1,0]
	v_pk_fma_f32 v[196:197], v[218:219], v[196:197], v[100:101]
	v_pk_mul_f32 v[216:217], v[98:99], v[180:181] op_sel_hi:[1,0]
	v_pk_fma_f32 v[196:197], v[36:37], v[92:93], v[196:197]
	v_pk_fma_f32 v[198:199], v[216:217], v[198:199], v[102:103]
	v_pk_fma_f32 v[192:193], v[214:215], v[192:193], v[196:197]
	v_pk_mul_f32 v[212:213], v[90:91], v[182:183] op_sel_hi:[1,0]
	v_pk_mul_f32 v[196:197], v[192:193], v[192:193]
	v_pk_fma_f32 v[198:199], v[38:39], v[94:95], v[198:199]
	v_pk_fma_f32 v[194:195], v[212:213], v[194:195], v[198:199]
	v_pk_mul_f32 v[198:199], v[194:195], v[194:195]
	v_pk_fma_f32 v[238:239], v[196:197], s[98:99], s[98:99] op_sel:[0,0,1] op_sel_hi:[1,0,1]
	v_pk_fma_f32 v[240:241], v[198:199], s[98:99], s[98:99] op_sel:[0,0,1] op_sel_hi:[1,0,1]
	v_pk_mul_f32 v[238:239], v[192:193], v[238:239]
	v_pk_mul_f32 v[240:241], v[194:195], v[240:241]
	v_pk_mul_f32 v[238:239], v[238:239], s[100:101] op_sel_hi:[1,0]
	v_pk_mul_f32 v[240:241], v[240:241], s[100:101] op_sel_hi:[1,0]
	v_exp_f32_e32 v238, v238
	v_exp_f32_e32 v240, v240
	v_exp_f32_e32 v239, v239
	v_exp_f32_e32 v241, v241
	v_pk_add_f32 v[238:239], v[238:239], s[98:99] op_sel:[0,1] op_sel_hi:[1,1]
	v_pk_add_f32 v[240:241], v[240:241], s[98:99] op_sel:[0,1] op_sel_hi:[1,1]
	v_rcp_f32_e32 v196, v238
	v_rcp_f32_e32 v198, v240
	v_rcp_f32_e32 v199, v241
	v_rcp_f32_e32 v197, v239
	v_pk_mul_f32 v[194:195], v[194:195], v[198:199]
	v_pk_mul_f32 v[198:199], v[82:83], v[180:181] op_sel_hi:[1,0]
	v_pk_mul_f32 v[180:181], v[80:81], v[180:181] op_sel_hi:[1,0]
	v_pk_mul_f32 v[192:193], v[192:193], v[196:197]
	v_pk_fma_f32 v[180:181], v[180:181], v[188:189], v[84:85]
	v_pk_mul_f32 v[196:197], v[74:75], v[182:183] op_sel_hi:[1,0]
	v_pk_mul_f32 v[182:183], v[72:73], v[182:183] op_sel_hi:[1,0]
	v_pk_fma_f32 v[180:181], v[28:29], v[76:77], v[180:181]
	v_pk_fma_f32 v[190:191], v[198:199], v[190:191], v[86:87]
	v_pk_fma_f32 v[180:181], v[182:183], v[184:185], v[180:181]
	v_pk_fma_f32 v[184:185], v[30:31], v[78:79], v[190:191]
	v_pk_mul_f32 v[182:183], v[180:181], v[180:181]
	v_pk_fma_f32 v[184:185], v[196:197], v[186:187], v[184:185]
	v_pk_mul_f32 v[186:187], v[184:185], v[184:185]
	v_pk_fma_f32 v[242:243], v[182:183], s[98:99], s[98:99] op_sel:[0,0,1] op_sel_hi:[1,0,1]
	v_pk_fma_f32 v[244:245], v[186:187], s[98:99], s[98:99] op_sel:[0,0,1] op_sel_hi:[1,0,1]
	v_pk_mul_f32 v[242:243], v[180:181], v[242:243]
	v_pk_mul_f32 v[244:245], v[184:185], v[244:245]
	v_pk_mul_f32 v[242:243], v[242:243], s[100:101] op_sel_hi:[1,0]
	v_pk_mul_f32 v[244:245], v[244:245], s[100:101] op_sel_hi:[1,0]
	v_exp_f32_e32 v242, v242
	v_exp_f32_e32 v244, v244
	v_exp_f32_e32 v243, v243
	v_exp_f32_e32 v245, v245
	v_pk_mul_f32 v[156:157], v[156:157], v[192:193]
	v_pk_add_f32 v[242:243], v[242:243], s[98:99] op_sel:[0,1] op_sel_hi:[1,1]
	v_pk_add_f32 v[244:245], v[244:245], s[98:99] op_sel:[0,1] op_sel_hi:[1,1]
	v_pk_mul_f32 v[158:159], v[158:159], v[194:195]
	v_rcp_f32_e32 v182, v242
	v_rcp_f32_e32 v186, v244
	v_rcp_f32_e32 v187, v245
	v_rcp_f32_e32 v183, v243
	v_ashrrev_i32_e32 v179, 31, v178
	v_pk_mul_f32 v[184:185], v[184:185], v[186:187]
	v_pk_mul_f32 v[180:181], v[180:181], v[182:183]
	v_pk_mul_f32 v[182:183], v[154:155], v[184:185]
	v_pk_mul_f32 v[154:155], v[152:153], v[180:181]
	v_cvt_pk_bf16_f32 v152, v156, v157
	v_lshlrev_b64 v[156:157], 13, v[178:179]
	v_lshl_add_u64 v[156:157], s[44:45], 0, v[156:157]
	v_lshl_add_u64 v[156:157], v[176:177], 1, v[156:157]
	v_cvt_pk_bf16_f32 v153, v158, v159
	v_cvt_pk_bf16_f32 v154, v154, v155
	v_cvt_pk_bf16_f32 v155, v182, v183
	global_store_dwordx4 v[156:157], v[152:155], off nt

; __device__ __forceinline__ unsigned cvt_pk_bf16(float lo, float hi) { unsigned r; asm volatile("v_cvt_pk_bf16_f32 %0, %1, %2" : "=v"(r) : "v"(lo), "v"(hi)); return r; }
; __device__ __forceinline__ float dpp_ror1(float v) { return __builtin_bit_cast(float, __builtin_amdgcn_update_dpp(0, __builtin_bit_cast(int, v), 0x121, 0xf, 0xf, false)); }
; __device__ __forceinline__ float dpp_ror15(float v) { return __builtin_bit_cast(float, __builtin_amdgcn_update_dpp(0, __builtin_bit_cast(int, v), 0x12F, 0xf, 0xf, false)); }
;     __device__ __forceinline__ void operator()(const f32x4 (&acc)[2][2][4][2], const Unit& u, int wr, int wc, int fr, int fq) const {
;     ...
;                 f32x4 res[2];
;                 const float fzp = zp ? 0.f : 1.f, fzn = zn ? 0.f : 1.f;
; #pragma unroll
;                 for (int n = 0; n < 2; ++n) {
;                     const f32x4 g = acc[ai][0][m][n], up = acc[ai][1][m][n];
;                     f32x4 tp = g, tn = g;
;                     if (!fix) { const f32x4 gm = (m > 0) ? acc[ai][0][m - 1][n] : acc[ai ^ 1][0][3][n], gx = (m < 3) ? acc[ai][0][m + 1][n] : acc[ai ^ 1][0][0][n];
;                         tp = (fr == 15) ? gm : g; tn = (fr == 0) ? gx : g; }
;                     f32x4 gp, gn;
; #pragma unroll
;                     for (int j = 0; j < 4; ++j) { gp[j] = dpp_ror1(tp[j]); gn[j] = dpp_ror15(tn[j]); }
;                     const f32x4 cv = (w0[n] * fzp) * gp + (w1[n] * g + ((w2[n] * fzn) * gn + bb[n]));
;                     const f32x4 inner = cv * (cv * cv * 0.044715f + 1.0f) * (-2.0f * 0.7978845608028654f * 1.4426950408889634f);
;                     f32x4 sg;
; #pragma unroll
;                     for (int j = 0; j < 4; ++j) sg[j] = __builtin_amdgcn_rcpf(1.0f + __builtin_amdgcn_exp2f(inner[j]));
;                     res[n] = cv * sg * up;
;                 }
;                 if (valid) { u32x4 w; w.x = cvt_pk_bf16(res[0][0], res[0][1]); w.y = cvt_pk_bf16(res[0][2], res[0][3]); w.z = cvt_pk_bf16(res[1][0], res[1][1]); w.w = cvt_pk_bf16(res[1][2], res[1][3]);
;                     __builtin_nontemporal_store(w, (u32x4*)(ACT + (size_t)grow * 4096 + ch0)); }
.LBB0_639:
	v_cndmask_b32_e64 v154, v142, v38, s[16:17]
	v_cndmask_b32_e64 v155, v141, v37, s[16:17]
	v_cndmask_b32_e64 v158, v142, v126, s[18:19]
	v_cndmask_b32_e64 v159, v141, v125, s[18:19]
	v_cndmask_b32_e64 v156, v140, v36, s[16:17]
	v_cndmask_b32_e64 v178, v140, v124, s[18:19]
	v_mov_b32_dpp v181, v155 row_ror:1 row_mask:0xf bank_mask:0xf
	v_mov_b32_dpp v185, v159 row_ror:15 row_mask:0xf bank_mask:0xf
	v_mov_b32_dpp v182, v154 row_ror:1 row_mask:0xf bank_mask:0xf
	v_mov_b32_dpp v186, v158 row_ror:15 row_mask:0xf bank_mask:0xf
	v_cndmask_b32_e64 v155, v136, v28, s[16:17]
	v_cndmask_b32_e64 v159, v136, v120, s[18:19]
	v_cndmask_b32_e64 v157, v143, v127, s[18:19]
	v_mov_b32_dpp v180, v156 row_ror:1 row_mask:0xf bank_mask:0xf
	v_mov_b32_dpp v184, v178 row_ror:15 row_mask:0xf bank_mask:0xf
	v_cndmask_b32_e64 v156, v137, v29, s[16:17]
	v_cndmask_b32_e64 v178, v137, v121, s[18:19]
	v_mov_b32_dpp v154, v155 row_ror:1 row_mask:0xf bank_mask:0xf
	v_mov_b32_dpp v158, v159 row_ror:15 row_mask:0xf bank_mask:0xf
	v_cndmask_b32_e64 v153, v143, v39, s[16:17]
	v_mov_b32_dpp v187, v157 row_ror:15 row_mask:0xf bank_mask:0xf
	v_cndmask_b32_e64 v157, v138, v30, s[16:17]
	v_cndmask_b32_e64 v179, v138, v122, s[18:19]
	v_mov_b32_dpp v155, v156 row_ror:1 row_mask:0xf bank_mask:0xf
	v_mov_b32_dpp v159, v178 row_ror:15 row_mask:0xf bank_mask:0xf
	v_mov_b32_dpp v183, v153 row_ror:1 row_mask:0xf bank_mask:0xf
	v_cndmask_b32_e64 v153, v139, v31, s[16:17]
	v_cndmask_b32_e64 v189, v139, v123, s[18:19]
	v_mov_b32_dpp v156, v157 row_ror:1 row_mask:0xf bank_mask:0xf
	v_mov_b32_dpp v178, v179 row_ror:15 row_mask:0xf bank_mask:0xf
	s_nop 0
	v_mov_b32_dpp v157, v153 row_ror:1 row_mask:0xf bank_mask:0xf
	v_mov_b32_dpp v179, v189 row_ror:15 row_mask:0xf bank_mask:0xf
	s_and_saveexec_b64 s[80:81], s[82:83]
	s_cbranch_execz .LBB0_641
	v_pk_fma_f32 v[184:185], v[96:97], v[184:185], v[100:101]
	v_pk_fma_f32 v[186:187], v[98:99], v[186:187], v[102:103]
	v_pk_fma_f32 v[184:185], v[140:141], v[92:93], v[184:185]
	v_pk_fma_f32 v[186:187], v[142:143], v[94:95], v[186:187]
	v_pk_fma_f32 v[180:181], v[88:89], v[180:181], v[184:185]
	v_pk_fma_f32 v[182:183], v[90:91], v[182:183], v[186:187]
	v_pk_mul_f32 v[184:185], v[180:181], v[180:181]
	v_pk_mul_f32 v[186:187], v[182:183], v[182:183]
	v_pk_fma_f32 v[238:239], v[184:185], s[98:99], s[98:99] op_sel:[0,0,1] op_sel_hi:[1,0,1]
	v_pk_fma_f32 v[240:241], v[186:187], s[98:99], s[98:99] op_sel:[0,0,1] op_sel_hi:[1,0,1]
	v_pk_mul_f32 v[238:239], v[180:181], v[238:239]
	v_pk_mul_f32 v[240:241], v[182:183], v[240:241]
	v_pk_mul_f32 v[238:239], v[238:239], s[100:101] op_sel_hi:[1,0]
	v_pk_mul_f32 v[240:241], v[240:241], s[100:101] op_sel_hi:[1,0]
	v_exp_f32_e32 v238, v238
	v_exp_f32_e32 v240, v240
	v_exp_f32_e32 v239, v239
	v_exp_f32_e32 v241, v241
	v_pk_fma_f32 v[158:159], v[80:81], v[158:159], v[84:85]
	v_pk_add_f32 v[238:239], v[238:239], s[98:99] op_sel:[0,1] op_sel_hi:[1,1]
	v_pk_add_f32 v[240:241], v[240:241], s[98:99] op_sel:[0,1] op_sel_hi:[1,1]
	v_pk_fma_f32 v[178:179], v[82:83], v[178:179], v[86:87]
	v_pk_fma_f32 v[158:159], v[136:137], v[76:77], v[158:159]
	v_rcp_f32_e32 v184, v238
	v_pk_fma_f32 v[154:155], v[72:73], v[154:155], v[158:159]
	v_rcp_f32_e32 v186, v240
	v_pk_mul_f32 v[158:159], v[154:155], v[154:155]
	v_rcp_f32_e32 v187, v241
	v_rcp_f32_e32 v185, v239
	v_pk_fma_f32 v[178:179], v[138:139], v[78:79], v[178:179]
	v_pk_mul_f32 v[180:181], v[180:181], v[184:185]
	v_pk_fma_f32 v[156:157], v[74:75], v[156:157], v[178:179]
	v_pk_mul_f32 v[178:179], v[156:157], v[156:157]
	v_pk_fma_f32 v[242:243], v[158:159], s[98:99], s[98:99] op_sel:[0,0,1] op_sel_hi:[1,0,1]
	v_pk_fma_f32 v[244:245], v[178:179], s[98:99], s[98:99] op_sel:[0,0,1] op_sel_hi:[1,0,1]
	v_pk_mul_f32 v[242:243], v[154:155], v[242:243]
	v_pk_mul_f32 v[244:245], v[156:157], v[244:245]
	v_pk_mul_f32 v[242:243], v[242:243], s[100:101] op_sel_hi:[1,0]
	v_pk_mul_f32 v[244:245], v[244:245], s[100:101] op_sel_hi:[1,0]
	v_exp_f32_e32 v242, v242
	v_exp_f32_e32 v244, v244
	v_exp_f32_e32 v243, v243
	v_exp_f32_e32 v245, v245
	v_pk_add_f32 v[242:243], v[242:243], s[98:99] op_sel:[0,1] op_sel_hi:[1,1]
	v_pk_add_f32 v[244:245], v[244:245], s[98:99] op_sel:[0,1] op_sel_hi:[1,1]
	v_rcp_f32_e32 v158, v242
	v_rcp_f32_e32 v178, v244
	v_rcp_f32_e32 v179, v245
	v_rcp_f32_e32 v159, v243
	v_pk_mul_f32 v[148:149], v[148:149], v[180:181]
	v_ashrrev_i32_e32 v153, 31, v152
	v_pk_mul_f32 v[156:157], v[156:157], v[178:179]
	v_pk_mul_f32 v[154:155], v[154:155], v[158:159]
	v_pk_mul_f32 v[156:157], v[146:147], v[156:157]
	v_pk_mul_f32 v[146:147], v[144:145], v[154:155]
	v_cvt_pk_bf16_f32 v144, v148, v149
	v_lshlrev_b64 v[148:149], 13, v[152:153]
	v_lshl_add_u64 v[148:149], s[44:45], 0, v[148:149]
	v_pk_mul_f32 v[182:183], v[182:183], v[186:187]
	v_lshl_add_u64 v[148:149], v[176:177], 1, v[148:149]
	v_pk_mul_f32 v[150:151], v[150:151], v[182:183]
	s_nop 0
	v_cvt_pk_bf16_f32 v145, v150, v151
	v_cvt_pk_bf16_f32 v146, v146, v147
	v_cvt_pk_bf16_f32 v147, v156, v157
	global_store_dwordx4 v[148:149], v[144:147], off nt

; __device__ __forceinline__ unsigned cvt_pk_bf16(float lo, float hi) { unsigned r; asm volatile("v_cvt_pk_bf16_f32 %0, %1, %2" : "=v"(r) : "v"(lo), "v"(hi)); return r; }
; __device__ __forceinline__ float dpp_ror1(float v) { return __builtin_bit_cast(float, __builtin_amdgcn_update_dpp(0, __builtin_bit_cast(int, v), 0x121, 0xf, 0xf, false)); }
; __device__ __forceinline__ float dpp_ror15(float v) { return __builtin_bit_cast(float, __builtin_amdgcn_update_dpp(0, __builtin_bit_cast(int, v), 0x12F, 0xf, 0xf, false)); }
;     __device__ __forceinline__ void operator()(const f32x4 (&acc)[2][2][4][2], const Unit& u, int wr, int wc, int fr, int fq) const {
;     ...
;                 f32x4 res[2];
;                 const float fzp = zp ? 0.f : 1.f, fzn = zn ? 0.f : 1.f;
; #pragma unroll
;                 for (int n = 0; n < 2; ++n) {
;                     const f32x4 g = acc[ai][0][m][n], up = acc[ai][1][m][n];
;                     f32x4 tp = g, tn = g;
;                     if (!fix) { const f32x4 gm = (m > 0) ? acc[ai][0][m - 1][n] : acc[ai ^ 1][0][3][n], gx = (m < 3) ? acc[ai][0][m + 1][n] : acc[ai ^ 1][0][0][n];
;                         tp = (fr == 15) ? gm : g; tn = (fr == 0) ? gx : g; }
;                     f32x4 gp, gn;
; #pragma unroll
;                     for (int j = 0; j < 4; ++j) { gp[j] = dpp_ror1(tp[j]); gn[j] = dpp_ror15(tn[j]); }
;                     const f32x4 cv = (w0[n] * fzp) * gp + (w1[n] * g + ((w2[n] * fzn) * gn + bb[n]));
;                     const f32x4 inner = cv * (cv * cv * 0.044715f + 1.0f) * (-2.0f * 0.7978845608028654f * 1.4426950408889634f);
;                     f32x4 sg;
; #pragma unroll
;                     for (int j = 0; j < 4; ++j) sg[j] = __builtin_amdgcn_rcpf(1.0f + __builtin_amdgcn_exp2f(inner[j]));
;                     res[n] = cv * sg * up;
;                 }
;                 if (valid) { u32x4 w; w.x = cvt_pk_bf16(res[0][0], res[0][1]); w.y = cvt_pk_bf16(res[0][2], res[0][3]); w.z = cvt_pk_bf16(res[1][0], res[1][1]); w.w = cvt_pk_bf16(res[1][2], res[1][3]);
;                     __builtin_nontemporal_store(w, (u32x4*)(ACT + (size_t)grow * 4096 + ch0)); }
.LBB0_647:
	v_cndmask_b32_e64 v149, v126, v110, s[18:19]
	v_cndmask_b32_e64 v143, v127, v143, s[16:17]
	v_cndmask_b32_e64 v147, v124, v108, s[18:19]
	v_mov_b32_dpp v152, v149 row_ror:15 row_mask:0xf bank_mask:0xf
	v_cndmask_b32_e64 v141, v125, v141, s[16:17]
	v_mov_b32_dpp v149, v143 row_ror:1 row_mask:0xf bank_mask:0xf
	v_cndmask_b32_e64 v143, v123, v139, s[16:17]
	v_cndmask_b32_e64 v139, v122, v138, s[16:17]
	v_cndmask_b32_e64 v138, v121, v137, s[16:17]
	v_cndmask_b32_e64 v137, v120, v136, s[16:17]
	v_cndmask_b32_e64 v140, v124, v140, s[16:17]
	v_cndmask_b32_e64 v148, v125, v109, s[18:19]
	v_mov_b32_dpp v150, v147 row_ror:15 row_mask:0xf bank_mask:0xf
	v_mov_b32_dpp v136, v137 row_ror:1 row_mask:0xf bank_mask:0xf
	v_cndmask_b32_e64 v142, v126, v142, s[16:17]
	v_mov_b32_dpp v146, v140 row_ror:1 row_mask:0xf bank_mask:0xf
	v_mov_b32_dpp v147, v141 row_ror:1 row_mask:0xf bank_mask:0xf
	v_mov_b32_dpp v151, v148 row_ror:15 row_mask:0xf bank_mask:0xf
	v_cndmask_b32_e64 v141, v120, v104, s[18:19]
	v_mov_b32_dpp v137, v138 row_ror:1 row_mask:0xf bank_mask:0xf
	v_cndmask_b32_e64 v145, v127, v111, s[18:19]
	v_mov_b32_dpp v148, v142 row_ror:1 row_mask:0xf bank_mask:0xf
	v_cndmask_b32_e64 v142, v121, v105, s[18:19]
	v_mov_b32_dpp v140, v141 row_ror:15 row_mask:0xf bank_mask:0xf
	v_mov_b32_dpp v138, v139 row_ror:1 row_mask:0xf bank_mask:0xf
	v_mov_b32_dpp v153, v145 row_ror:15 row_mask:0xf bank_mask:0xf
	v_cndmask_b32_e64 v145, v123, v107, s[18:19]
	v_cndmask_b32_e64 v154, v122, v106, s[18:19]
	v_mov_b32_dpp v141, v142 row_ror:15 row_mask:0xf bank_mask:0xf
	v_mov_b32_dpp v139, v143 row_ror:1 row_mask:0xf bank_mask:0xf
	v_mov_b32_dpp v142, v154 row_ror:15 row_mask:0xf bank_mask:0xf
	s_nop 0
	v_mov_b32_dpp v143, v145 row_ror:15 row_mask:0xf bank_mask:0xf
	s_and_saveexec_b64 s[80:81], s[82:83]
	s_cbranch_execz .LBB0_649
	v_pk_fma_f32 v[150:151], v[96:97], v[150:151], v[100:101]
	v_pk_fma_f32 v[152:153], v[98:99], v[152:153], v[102:103]
	v_pk_fma_f32 v[150:151], v[124:125], v[92:93], v[150:151]
	v_pk_fma_f32 v[152:153], v[126:127], v[94:95], v[152:153]
	v_pk_fma_f32 v[146:147], v[88:89], v[146:147], v[150:151]
	v_pk_fma_f32 v[148:149], v[90:91], v[148:149], v[152:153]
	v_pk_mul_f32 v[150:151], v[146:147], v[146:147]
	v_pk_fma_f32 v[142:143], v[82:83], v[142:143], v[86:87]
	v_pk_fma_f32 v[140:141], v[80:81], v[140:141], v[84:85]
	v_pk_mul_f32 v[152:153], v[148:149], v[148:149]
	v_pk_fma_f32 v[238:239], v[150:151], s[98:99], s[98:99] op_sel:[0,0,1] op_sel_hi:[1,0,1]
	v_pk_fma_f32 v[240:241], v[152:153], s[98:99], s[98:99] op_sel:[0,0,1] op_sel_hi:[1,0,1]
	v_pk_mul_f32 v[238:239], v[146:147], v[238:239]
	v_pk_mul_f32 v[240:241], v[148:149], v[240:241]
	v_pk_mul_f32 v[238:239], v[238:239], s[100:101] op_sel_hi:[1,0]
	v_pk_mul_f32 v[240:241], v[240:241], s[100:101] op_sel_hi:[1,0]
	v_exp_f32_e32 v238, v238
	v_exp_f32_e32 v240, v240
	v_exp_f32_e32 v239, v239
	v_exp_f32_e32 v241, v241
	v_pk_fma_f32 v[140:141], v[120:121], v[76:77], v[140:141]
	v_pk_add_f32 v[238:239], v[238:239], s[98:99] op_sel:[0,1] op_sel_hi:[1,1]
	v_pk_add_f32 v[240:241], v[240:241], s[98:99] op_sel:[0,1] op_sel_hi:[1,1]
	v_pk_fma_f32 v[142:143], v[122:123], v[78:79], v[142:143]
	v_rcp_f32_e32 v150, v238
	v_pk_fma_f32 v[136:137], v[72:73], v[136:137], v[140:141]
	v_pk_fma_f32 v[138:139], v[74:75], v[138:139], v[142:143]
	v_pk_mul_f32 v[140:141], v[136:137], v[136:137]
	v_pk_mul_f32 v[142:143], v[138:139], v[138:139]
	v_pk_fma_f32 v[242:243], v[140:141], s[98:99], s[98:99] op_sel:[0,0,1] op_sel_hi:[1,0,1]
	v_pk_fma_f32 v[244:245], v[142:143], s[98:99], s[98:99] op_sel:[0,0,1] op_sel_hi:[1,0,1]
	v_pk_mul_f32 v[242:243], v[136:137], v[242:243]
	v_pk_mul_f32 v[244:245], v[138:139], v[244:245]
	v_pk_mul_f32 v[242:243], v[242:243], s[100:101] op_sel_hi:[1,0]
	v_pk_mul_f32 v[244:245], v[244:245], s[100:101] op_sel_hi:[1,0]
	v_exp_f32_e32 v242, v242
	v_exp_f32_e32 v244, v244
	v_exp_f32_e32 v243, v243
	v_exp_f32_e32 v245, v245
	v_rcp_f32_e32 v152, v240
	v_rcp_f32_e32 v153, v241
	v_rcp_f32_e32 v151, v239
	v_pk_add_f32 v[242:243], v[242:243], s[98:99] op_sel:[0,1] op_sel_hi:[1,1]
	v_pk_add_f32 v[244:245], v[244:245], s[98:99] op_sel:[0,1] op_sel_hi:[1,1]
	v_rcp_f32_e32 v140, v242
	v_rcp_f32_e32 v142, v244
	v_rcp_f32_e32 v143, v245
	v_rcp_f32_e32 v141, v243
	v_pk_mul_f32 v[146:147], v[146:147], v[150:151]
	v_ashrrev_i32_e32 v145, 31, v144
	v_pk_mul_f32 v[132:133], v[132:133], v[146:147]
	v_pk_mul_f32 v[138:139], v[138:139], v[142:143]
	v_pk_mul_f32 v[136:137], v[136:137], v[140:141]
	v_pk_mul_f32 v[138:139], v[130:131], v[138:139]
	v_pk_mul_f32 v[130:131], v[128:129], v[136:137]
	v_cvt_pk_bf16_f32 v128, v132, v133
	v_lshlrev_b64 v[132:133], 13, v[144:145]
	v_lshl_add_u64 v[132:133], s[44:45], 0, v[132:133]
	v_pk_mul_f32 v[148:149], v[148:149], v[152:153]
	v_lshl_add_u64 v[132:133], v[176:177], 1, v[132:133]
	v_pk_mul_f32 v[134:135], v[134:135], v[148:149]
	s_nop 0
	v_cvt_pk_bf16_f32 v129, v134, v135
	v_cvt_pk_bf16_f32 v130, v130, v131
	v_cvt_pk_bf16_f32 v131, v138, v139
	global_store_dwordx4 v[132:133], v[128:131], off nt

; __device__ __forceinline__ unsigned cvt_pk_bf16(float lo, float hi) { unsigned r; asm volatile("v_cvt_pk_bf16_f32 %0, %1, %2" : "=v"(r) : "v"(lo), "v"(hi)); return r; }
; __device__ __forceinline__ float dpp_ror1(float v) { return __builtin_bit_cast(float, __builtin_amdgcn_update_dpp(0, __builtin_bit_cast(int, v), 0x121, 0xf, 0xf, false)); }
; __device__ __forceinline__ float dpp_ror15(float v) { return __builtin_bit_cast(float, __builtin_amdgcn_update_dpp(0, __builtin_bit_cast(int, v), 0x12F, 0xf, 0xf, false)); }
;     __device__ __forceinline__ void operator()(const f32x4 (&acc)[2][2][4][2], const Unit& u, int wr, int wc, int fr, int fq) const {
;     ...
;                 f32x4 res[2];
;                 const float fzp = zp ? 0.f : 1.f, fzn = zn ? 0.f : 1.f;
; #pragma unroll
;                 for (int n = 0; n < 2; ++n) {
;                     const f32x4 g = acc[ai][0][m][n], up = acc[ai][1][m][n];
;                     f32x4 tp = g, tn = g;
;                     if (!fix) { const f32x4 gm = (m > 0) ? acc[ai][0][m - 1][n] : acc[ai ^ 1][0][3][n], gx = (m < 3) ? acc[ai][0][m + 1][n] : acc[ai ^ 1][0][0][n];
;                         tp = (fr == 15) ? gm : g; tn = (fr == 0) ? gx : g; }
;                     f32x4 gp, gn;
; #pragma unroll
;                     for (int j = 0; j < 4; ++j) { gp[j] = dpp_ror1(tp[j]); gn[j] = dpp_ror15(tn[j]); }
;                     const f32x4 cv = (w0[n] * fzp) * gp + (w1[n] * g + ((w2[n] * fzn) * gn + bb[n]));
;                     const f32x4 inner = cv * (cv * cv * 0.044715f + 1.0f) * (-2.0f * 0.7978845608028654f * 1.4426950408889634f);
;                     f32x4 sg;
; #pragma unroll
;                     for (int j = 0; j < 4; ++j) sg[j] = __builtin_amdgcn_rcpf(1.0f + __builtin_amdgcn_exp2f(inner[j]));
;                     res[n] = cv * sg * up;
;                 }
;                 if (valid) { u32x4 w; w.x = cvt_pk_bf16(res[0][0], res[0][1]); w.y = cvt_pk_bf16(res[0][2], res[0][3]); w.z = cvt_pk_bf16(res[1][0], res[1][1]); w.w = cvt_pk_bf16(res[1][2], res[1][3]);
;                     __builtin_nontemporal_store(w, (u32x4*)(ACT + (size_t)grow * 4096 + ch0)); }
.LBB0_655:
	v_cndmask_b32_e64 v133, v110, v62, s[18:19]
	v_cndmask_b32_e64 v127, v111, v127, s[16:17]
	v_cndmask_b32_e64 v131, v108, v60, s[18:19]
	v_mov_b32_dpp v136, v133 row_ror:15 row_mask:0xf bank_mask:0xf
	v_cndmask_b32_e64 v125, v109, v125, s[16:17]
	v_mov_b32_dpp v133, v127 row_ror:1 row_mask:0xf bank_mask:0xf
	v_cndmask_b32_e64 v127, v107, v123, s[16:17]
	v_cndmask_b32_e64 v123, v106, v122, s[16:17]
	v_cndmask_b32_e64 v122, v105, v121, s[16:17]
	v_cndmask_b32_e64 v121, v104, v120, s[16:17]
	v_cndmask_b32_e64 v124, v108, v124, s[16:17]
	v_cndmask_b32_e64 v132, v109, v61, s[18:19]
	v_mov_b32_dpp v134, v131 row_ror:15 row_mask:0xf bank_mask:0xf
	v_mov_b32_dpp v120, v121 row_ror:1 row_mask:0xf bank_mask:0xf
	v_cndmask_b32_e64 v126, v110, v126, s[16:17]
	v_mov_b32_dpp v130, v124 row_ror:1 row_mask:0xf bank_mask:0xf
	v_mov_b32_dpp v131, v125 row_ror:1 row_mask:0xf bank_mask:0xf
	v_mov_b32_dpp v135, v132 row_ror:15 row_mask:0xf bank_mask:0xf
	v_cndmask_b32_e64 v125, v104, v56, s[18:19]
	v_mov_b32_dpp v121, v122 row_ror:1 row_mask:0xf bank_mask:0xf
	v_cndmask_b32_e64 v129, v111, v63, s[18:19]
	v_mov_b32_dpp v132, v126 row_ror:1 row_mask:0xf bank_mask:0xf
	v_cndmask_b32_e64 v126, v105, v57, s[18:19]
	v_mov_b32_dpp v124, v125 row_ror:15 row_mask:0xf bank_mask:0xf
	v_mov_b32_dpp v122, v123 row_ror:1 row_mask:0xf bank_mask:0xf
	v_mov_b32_dpp v137, v129 row_ror:15 row_mask:0xf bank_mask:0xf
	v_cndmask_b32_e64 v129, v107, v59, s[18:19]
	v_cndmask_b32_e64 v138, v106, v58, s[18:19]
	v_mov_b32_dpp v125, v126 row_ror:15 row_mask:0xf bank_mask:0xf
	v_mov_b32_dpp v123, v127 row_ror:1 row_mask:0xf bank_mask:0xf
	v_mov_b32_dpp v126, v138 row_ror:15 row_mask:0xf bank_mask:0xf
	s_nop 0
	v_mov_b32_dpp v127, v129 row_ror:15 row_mask:0xf bank_mask:0xf
	s_and_saveexec_b64 s[80:81], s[82:83]
	s_cbranch_execz .LBB0_657
	v_pk_fma_f32 v[134:135], v[96:97], v[134:135], v[100:101]
	v_pk_fma_f32 v[136:137], v[98:99], v[136:137], v[102:103]
	v_pk_fma_f32 v[134:135], v[108:109], v[92:93], v[134:135]
	v_pk_fma_f32 v[136:137], v[110:111], v[94:95], v[136:137]
	v_pk_fma_f32 v[130:131], v[88:89], v[130:131], v[134:135]
	v_pk_fma_f32 v[132:133], v[90:91], v[132:133], v[136:137]
	v_pk_mul_f32 v[134:135], v[130:131], v[130:131]
	v_pk_fma_f32 v[126:127], v[82:83], v[126:127], v[86:87]
	v_pk_fma_f32 v[124:125], v[80:81], v[124:125], v[84:85]
	v_pk_mul_f32 v[136:137], v[132:133], v[132:133]
	v_pk_fma_f32 v[238:239], v[134:135], s[98:99], s[98:99] op_sel:[0,0,1] op_sel_hi:[1,0,1]
	v_pk_fma_f32 v[240:241], v[136:137], s[98:99], s[98:99] op_sel:[0,0,1] op_sel_hi:[1,0,1]
	v_pk_mul_f32 v[238:239], v[130:131], v[238:239]
	v_pk_mul_f32 v[240:241], v[132:133], v[240:241]
	v_pk_mul_f32 v[238:239], v[238:239], s[100:101] op_sel_hi:[1,0]
	v_pk_mul_f32 v[240:241], v[240:241], s[100:101] op_sel_hi:[1,0]
	v_exp_f32_e32 v238, v238
	v_exp_f32_e32 v240, v240
	v_exp_f32_e32 v239, v239
	v_exp_f32_e32 v241, v241
	v_pk_fma_f32 v[124:125], v[104:105], v[76:77], v[124:125]
	v_pk_add_f32 v[238:239], v[238:239], s[98:99] op_sel:[0,1] op_sel_hi:[1,1]
	v_pk_add_f32 v[240:241], v[240:241], s[98:99] op_sel:[0,1] op_sel_hi:[1,1]
	v_pk_fma_f32 v[126:127], v[106:107], v[78:79], v[126:127]
	v_rcp_f32_e32 v134, v238
	v_pk_fma_f32 v[120:121], v[72:73], v[120:121], v[124:125]
	v_pk_fma_f32 v[122:123], v[74:75], v[122:123], v[126:127]
	v_pk_mul_f32 v[124:125], v[120:121], v[120:121]
	v_pk_mul_f32 v[126:127], v[122:123], v[122:123]
	v_pk_fma_f32 v[242:243], v[124:125], s[98:99], s[98:99] op_sel:[0,0,1] op_sel_hi:[1,0,1]
	v_pk_fma_f32 v[244:245], v[126:127], s[98:99], s[98:99] op_sel:[0,0,1] op_sel_hi:[1,0,1]
	v_pk_mul_f32 v[242:243], v[120:121], v[242:243]
	v_pk_mul_f32 v[244:245], v[122:123], v[244:245]
	v_pk_mul_f32 v[242:243], v[242:243], s[100:101] op_sel_hi:[1,0]
	v_pk_mul_f32 v[244:245], v[244:245], s[100:101] op_sel_hi:[1,0]
	v_exp_f32_e32 v242, v242
	v_exp_f32_e32 v244, v244
	v_exp_f32_e32 v243, v243
	v_exp_f32_e32 v245, v245
	v_rcp_f32_e32 v136, v240
	v_rcp_f32_e32 v137, v241
	v_rcp_f32_e32 v135, v239
	v_pk_add_f32 v[242:243], v[242:243], s[98:99] op_sel:[0,1] op_sel_hi:[1,1]
	v_pk_add_f32 v[244:245], v[244:245], s[98:99] op_sel:[0,1] op_sel_hi:[1,1]
	v_rcp_f32_e32 v124, v242
	v_rcp_f32_e32 v126, v244
	v_rcp_f32_e32 v127, v245
	v_rcp_f32_e32 v125, v243
	v_pk_mul_f32 v[130:131], v[130:131], v[134:135]
	v_ashrrev_i32_e32 v129, 31, v128
	v_pk_mul_f32 v[116:117], v[116:117], v[130:131]
	v_pk_mul_f32 v[122:123], v[122:123], v[126:127]
	v_pk_mul_f32 v[120:121], v[120:121], v[124:125]
	v_pk_mul_f32 v[122:123], v[114:115], v[122:123]
	v_pk_mul_f32 v[114:115], v[112:113], v[120:121]
	v_cvt_pk_bf16_f32 v112, v116, v117
	v_lshlrev_b64 v[116:117], 13, v[128:129]
	v_lshl_add_u64 v[116:117], s[44:45], 0, v[116:117]
	v_pk_mul_f32 v[132:133], v[132:133], v[136:137]
	v_lshl_add_u64 v[116:117], v[176:177], 1, v[116:117]
	v_pk_mul_f32 v[118:119], v[118:119], v[132:133]
	s_nop 0
	v_cvt_pk_bf16_f32 v113, v118, v119
	v_cvt_pk_bf16_f32 v114, v114, v115
	v_cvt_pk_bf16_f32 v115, v122, v123
	global_store_dwordx4 v[116:117], v[112:115], off nt

; __device__ __forceinline__ unsigned cvt_pk_bf16(float lo, float hi) { unsigned r; asm volatile("v_cvt_pk_bf16_f32 %0, %1, %2" : "=v"(r) : "v"(lo), "v"(hi)); return r; }
; __device__ __forceinline__ float dpp_ror1(float v) { return __builtin_bit_cast(float, __builtin_amdgcn_update_dpp(0, __builtin_bit_cast(int, v), 0x121, 0xf, 0xf, false)); }
; __device__ __forceinline__ float dpp_ror15(float v) { return __builtin_bit_cast(float, __builtin_amdgcn_update_dpp(0, __builtin_bit_cast(int, v), 0x12F, 0xf, 0xf, false)); }
;     __device__ __forceinline__ void operator()(const f32x4 (&acc)[2][2][4][2], const Unit& u, int wr, int wc, int fr, int fq) const {
;     ...
;                 f32x4 res[2];
;                 const float fzp = zp ? 0.f : 1.f, fzn = zn ? 0.f : 1.f;
; #pragma unroll
;                 for (int n = 0; n < 2; ++n) {
;                     const f32x4 g = acc[ai][0][m][n], up = acc[ai][1][m][n];
;                     f32x4 tp = g, tn = g;
;                     if (!fix) { const f32x4 gm = (m > 0) ? acc[ai][0][m - 1][n] : acc[ai ^ 1][0][3][n], gx = (m < 3) ? acc[ai][0][m + 1][n] : acc[ai ^ 1][0][0][n];
;                         tp = (fr == 15) ? gm : g; tn = (fr == 0) ? gx : g; }
;                     f32x4 gp, gn;
; #pragma unroll
;                     for (int j = 0; j < 4; ++j) { gp[j] = dpp_ror1(tp[j]); gn[j] = dpp_ror15(tn[j]); }
;                     const f32x4 cv = (w0[n] * fzp) * gp + (w1[n] * g + ((w2[n] * fzn) * gn + bb[n]));
;                     const f32x4 inner = cv * (cv * cv * 0.044715f + 1.0f) * (-2.0f * 0.7978845608028654f * 1.4426950408889634f);
;                     f32x4 sg;
; #pragma unroll
;                     for (int j = 0; j < 4; ++j) sg[j] = __builtin_amdgcn_rcpf(1.0f + __builtin_amdgcn_exp2f(inner[j]));
;                     res[n] = cv * sg * up;
;                 }
;                 if (valid) { u32x4 w; w.x = cvt_pk_bf16(res[0][0], res[0][1]); w.y = cvt_pk_bf16(res[0][2], res[0][3]); w.z = cvt_pk_bf16(res[1][0], res[1][1]); w.w = cvt_pk_bf16(res[1][2], res[1][3]);
;                     __builtin_nontemporal_store(w, (u32x4*)(ACT + (size_t)grow * 4096 + ch0)); }
.LBB0_661:
	v_cndmask_b32_e64 v111, v63, v111, s[16:17]
	v_cndmask_b32_e64 v119, v60, v44, s[18:19]
	v_mov_b32_e32 v122, 0
	v_mov_b32_dpp v121, v111 row_ror:1 row_mask:0xf bank_mask:0xf
	v_cndmask_b32_e64 v111, v59, v107, s[16:17]
	v_cndmask_b32_e64 v107, v58, v106, s[16:17]
	v_cndmask_b32_e64 v106, v57, v105, s[16:17]
	v_cndmask_b32_e64 v105, v56, v104, s[16:17]
	v_cndmask_b32_e64 v109, v61, v109, s[16:17]
	v_cndmask_b32_e64 v108, v60, v108, s[16:17]
	v_mov_b32_dpp v122, v119 row_ror:15 row_mask:0xf bank_mask:0xf
	v_mov_b32_dpp v104, v105 row_ror:1 row_mask:0xf bank_mask:0xf
	v_cndmask_b32_e64 v110, v62, v110, s[16:17]
	v_mov_b32_dpp v118, v108 row_ror:1 row_mask:0xf bank_mask:0xf
	v_mov_b32_dpp v119, v109 row_ror:1 row_mask:0xf bank_mask:0xf
	v_cndmask_b32_e64 v109, v56, v40, s[18:19]
	v_mov_b32_dpp v105, v106 row_ror:1 row_mask:0xf bank_mask:0xf
	v_cndmask_b32_e64 v113, v63, v47, s[18:19]
	v_cndmask_b32_e64 v115, v62, v46, s[18:19]
	v_mov_b32_dpp v120, v110 row_ror:1 row_mask:0xf bank_mask:0xf
	v_cndmask_b32_e64 v110, v57, v41, s[18:19]
	v_mov_b32_dpp v108, v109 row_ror:15 row_mask:0xf bank_mask:0xf
	v_mov_b32_dpp v106, v107 row_ror:1 row_mask:0xf bank_mask:0xf
	v_cndmask_b32_e64 v117, v61, v45, s[18:19]
	v_mov_b32_dpp v124, v115 row_ror:15 row_mask:0xf bank_mask:0xf
	v_mov_b32_dpp v125, v113 row_ror:15 row_mask:0xf bank_mask:0xf
	v_cndmask_b32_e64 v113, v59, v43, s[18:19]
	v_cndmask_b32_e64 v115, v58, v42, s[18:19]
	v_mov_b32_dpp v109, v110 row_ror:15 row_mask:0xf bank_mask:0xf
	v_mov_b32_dpp v107, v111 row_ror:1 row_mask:0xf bank_mask:0xf
	v_mov_b32_dpp v123, v117 row_ror:15 row_mask:0xf bank_mask:0xf
	v_mov_b32_dpp v110, v115 row_ror:15 row_mask:0xf bank_mask:0xf
	v_mov_b32_dpp v111, v113 row_ror:15 row_mask:0xf bank_mask:0xf
	s_and_saveexec_b64 s[80:81], s[82:83]
	s_cbranch_execz .LBB0_663
	v_pk_mul_f32 v[132:133], v[96:97], v[114:115] op_sel_hi:[1,0]
	v_pk_mul_f32 v[128:129], v[88:89], v[116:117] op_sel_hi:[1,0]
	v_pk_fma_f32 v[122:123], v[132:133], v[122:123], v[100:101]
	v_pk_mul_f32 v[130:131], v[98:99], v[114:115] op_sel_hi:[1,0]
	v_pk_fma_f32 v[122:123], v[60:61], v[92:93], v[122:123]
	v_pk_fma_f32 v[124:125], v[130:131], v[124:125], v[102:103]
	v_pk_fma_f32 v[118:119], v[128:129], v[118:119], v[122:123]
	v_pk_mul_f32 v[126:127], v[90:91], v[116:117] op_sel_hi:[1,0]
	v_pk_mul_f32 v[122:123], v[118:119], v[118:119]
	v_pk_fma_f32 v[124:125], v[62:63], v[94:95], v[124:125]
	v_pk_fma_f32 v[120:121], v[126:127], v[120:121], v[124:125]
	v_pk_mul_f32 v[124:125], v[120:121], v[120:121]
	v_pk_fma_f32 v[238:239], v[122:123], s[98:99], s[98:99] op_sel:[0,0,1] op_sel_hi:[1,0,1]
	v_pk_fma_f32 v[240:241], v[124:125], s[98:99], s[98:99] op_sel:[0,0,1] op_sel_hi:[1,0,1]
	v_pk_mul_f32 v[238:239], v[118:119], v[238:239]
	v_pk_mul_f32 v[240:241], v[120:121], v[240:241]
	v_pk_mul_f32 v[238:239], v[238:239], s[100:101] op_sel_hi:[1,0]
	v_pk_mul_f32 v[240:241], v[240:241], s[100:101] op_sel_hi:[1,0]
	v_exp_f32_e32 v238, v238
	v_exp_f32_e32 v240, v240
	v_exp_f32_e32 v239, v239
	v_exp_f32_e32 v241, v241
	v_pk_add_f32 v[238:239], v[238:239], s[98:99] op_sel:[0,1] op_sel_hi:[1,1]
	v_pk_add_f32 v[240:241], v[240:241], s[98:99] op_sel:[0,1] op_sel_hi:[1,1]
	v_rcp_f32_e32 v122, v238
	v_rcp_f32_e32 v124, v240
	v_rcp_f32_e32 v125, v241
	v_rcp_f32_e32 v123, v239
	v_ashrrev_i32_e32 v113, 31, v112
	v_pk_mul_f32 v[120:121], v[120:121], v[124:125]
	v_pk_mul_f32 v[124:125], v[82:83], v[114:115] op_sel_hi:[1,0]
	v_pk_mul_f32 v[114:115], v[80:81], v[114:115] op_sel_hi:[1,0]
	v_pk_fma_f32 v[110:111], v[124:125], v[110:111], v[86:87]
	v_pk_fma_f32 v[108:109], v[114:115], v[108:109], v[84:85]
	v_pk_mul_f32 v[118:119], v[118:119], v[122:123]
	v_pk_mul_f32 v[122:123], v[74:75], v[116:117] op_sel_hi:[1,0]
	v_pk_mul_f32 v[116:117], v[72:73], v[116:117] op_sel_hi:[1,0]
	v_pk_fma_f32 v[108:109], v[56:57], v[76:77], v[108:109]
	v_pk_fma_f32 v[110:111], v[58:59], v[78:79], v[110:111]
	v_pk_fma_f32 v[104:105], v[116:117], v[104:105], v[108:109]
	v_pk_fma_f32 v[106:107], v[122:123], v[106:107], v[110:111]
	v_pk_mul_f32 v[108:109], v[104:105], v[104:105]
	v_pk_mul_f32 v[110:111], v[106:107], v[106:107]
	v_pk_fma_f32 v[242:243], v[108:109], s[98:99], s[98:99] op_sel:[0,0,1] op_sel_hi:[1,0,1]
	v_pk_fma_f32 v[244:245], v[110:111], s[98:99], s[98:99] op_sel:[0,0,1] op_sel_hi:[1,0,1]
	v_pk_mul_f32 v[242:243], v[104:105], v[242:243]
	v_pk_mul_f32 v[244:245], v[106:107], v[244:245]
	v_pk_mul_f32 v[242:243], v[242:243], s[100:101] op_sel_hi:[1,0]
	v_pk_mul_f32 v[244:245], v[244:245], s[100:101] op_sel_hi:[1,0]
	v_exp_f32_e32 v242, v242
	v_exp_f32_e32 v244, v244
	v_exp_f32_e32 v243, v243
	v_exp_f32_e32 v245, v245
	v_pk_add_f32 v[242:243], v[242:243], s[98:99] op_sel:[0,1] op_sel_hi:[1,1]
	v_pk_add_f32 v[244:245], v[244:245], s[98:99] op_sel:[0,1] op_sel_hi:[1,1]
	v_rcp_f32_e32 v108, v242
	v_rcp_f32_e32 v110, v244
	v_rcp_f32_e32 v111, v245
	v_rcp_f32_e32 v109, v243
	v_pk_mul_f32 v[68:69], v[68:69], v[118:119]
	v_pk_mul_f32 v[70:71], v[70:71], v[120:121]
	v_pk_mul_f32 v[106:107], v[106:107], v[110:111]
	v_pk_mul_f32 v[104:105], v[104:105], v[108:109]
	v_pk_mul_f32 v[106:107], v[66:67], v[106:107]
	v_pk_mul_f32 v[66:67], v[64:65], v[104:105]
	v_cvt_pk_bf16_f32 v64, v68, v69
	v_lshlrev_b64 v[68:69], 13, v[112:113]
	v_lshl_add_u64 v[68:69], s[44:45], 0, v[68:69]
	v_lshl_add_u64 v[68:69], v[176:177], 1, v[68:69]
	v_cvt_pk_bf16_f32 v65, v70, v71
	v_cvt_pk_bf16_f32 v66, v66, v67
	v_cvt_pk_bf16_f32 v67, v106, v107
	global_store_dwordx4 v[68:69], v[64:67], off nt

; __device__ __forceinline__ unsigned cvt_pk_bf16(float lo, float hi) { unsigned r; asm volatile("v_cvt_pk_bf16_f32 %0, %1, %2" : "=v"(r) : "v"(lo), "v"(hi)); return r; }
; __device__ __forceinline__ float dpp_ror1(float v) { return __builtin_bit_cast(float, __builtin_amdgcn_update_dpp(0, __builtin_bit_cast(int, v), 0x121, 0xf, 0xf, false)); }
; __device__ __forceinline__ float dpp_ror15(float v) { return __builtin_bit_cast(float, __builtin_amdgcn_update_dpp(0, __builtin_bit_cast(int, v), 0x12F, 0xf, 0xf, false)); }
;     __device__ __forceinline__ void operator()(const f32x4 (&acc)[2][2][4][2], const Unit& u, int wr, int wc, int fr, int fq) const {
;     ...
;                 f32x4 res[2];
;                 const float fzp = zp ? 0.f : 1.f, fzn = zn ? 0.f : 1.f;
; #pragma unroll
;                 for (int n = 0; n < 2; ++n) {
;                     const f32x4 g = acc[ai][0][m][n], up = acc[ai][1][m][n];
;                     f32x4 tp = g, tn = g;
;                     if (!fix) { const f32x4 gm = (m > 0) ? acc[ai][0][m - 1][n] : acc[ai ^ 1][0][3][n], gx = (m < 3) ? acc[ai][0][m + 1][n] : acc[ai ^ 1][0][0][n];
;                         tp = (fr == 15) ? gm : g; tn = (fr == 0) ? gx : g; }
;                     f32x4 gp, gn;
; #pragma unroll
;                     for (int j = 0; j < 4; ++j) { gp[j] = dpp_ror1(tp[j]); gn[j] = dpp_ror15(tn[j]); }
;                     const f32x4 cv = (w0[n] * fzp) * gp + (w1[n] * g + ((w2[n] * fzn) * gn + bb[n]));
;                     const f32x4 inner = cv * (cv * cv * 0.044715f + 1.0f) * (-2.0f * 0.7978845608028654f * 1.4426950408889634f);
;                     f32x4 sg;
; #pragma unroll
;                     for (int j = 0; j < 4; ++j) sg[j] = __builtin_amdgcn_rcpf(1.0f + __builtin_amdgcn_exp2f(inner[j]));
;                     res[n] = cv * sg * up;
;                 }
;                 if (valid) { u32x4 w; w.x = cvt_pk_bf16(res[0][0], res[0][1]); w.y = cvt_pk_bf16(res[0][2], res[0][3]); w.z = cvt_pk_bf16(res[1][0], res[1][1]); w.w = cvt_pk_bf16(res[1][2], res[1][3]);
;                     __builtin_nontemporal_store(w, (u32x4*)(ACT + (size_t)grow * 4096 + ch0)); }
.LBB0_669:
	v_cndmask_b32_e64 v69, v46, v22, s[18:19]
	v_cndmask_b32_e64 v63, v47, v63, s[16:17]
	v_cndmask_b32_e64 v67, v44, v20, s[18:19]
	v_mov_b32_dpp v104, v69 row_ror:15 row_mask:0xf bank_mask:0xf
	v_cndmask_b32_e64 v61, v45, v61, s[16:17]
	v_mov_b32_dpp v69, v63 row_ror:1 row_mask:0xf bank_mask:0xf
	v_cndmask_b32_e64 v63, v43, v59, s[16:17]
	v_cndmask_b32_e64 v59, v42, v58, s[16:17]
	v_cndmask_b32_e64 v58, v41, v57, s[16:17]
	v_cndmask_b32_e64 v57, v40, v56, s[16:17]
	v_cndmask_b32_e64 v60, v44, v60, s[16:17]
	v_cndmask_b32_e64 v68, v45, v21, s[18:19]
	v_mov_b32_dpp v70, v67 row_ror:15 row_mask:0xf bank_mask:0xf
	v_mov_b32_dpp v56, v57 row_ror:1 row_mask:0xf bank_mask:0xf
	v_cndmask_b32_e64 v62, v46, v62, s[16:17]
	v_mov_b32_dpp v66, v60 row_ror:1 row_mask:0xf bank_mask:0xf
	v_mov_b32_dpp v67, v61 row_ror:1 row_mask:0xf bank_mask:0xf
	v_mov_b32_dpp v71, v68 row_ror:15 row_mask:0xf bank_mask:0xf
	v_cndmask_b32_e64 v61, v40, v16, s[18:19]
	v_mov_b32_dpp v57, v58 row_ror:1 row_mask:0xf bank_mask:0xf
	v_cndmask_b32_e64 v65, v47, v23, s[18:19]
	v_mov_b32_dpp v68, v62 row_ror:1 row_mask:0xf bank_mask:0xf
	v_cndmask_b32_e64 v62, v41, v17, s[18:19]
	v_mov_b32_dpp v60, v61 row_ror:15 row_mask:0xf bank_mask:0xf
	v_mov_b32_dpp v58, v59 row_ror:1 row_mask:0xf bank_mask:0xf
	v_mov_b32_dpp v105, v65 row_ror:15 row_mask:0xf bank_mask:0xf
	v_cndmask_b32_e64 v65, v43, v19, s[18:19]
	v_cndmask_b32_e64 v107, v42, v18, s[18:19]
	v_mov_b32_dpp v61, v62 row_ror:15 row_mask:0xf bank_mask:0xf
	v_mov_b32_dpp v59, v63 row_ror:1 row_mask:0xf bank_mask:0xf
	v_mov_b32_dpp v62, v107 row_ror:15 row_mask:0xf bank_mask:0xf
	s_nop 0
	v_mov_b32_dpp v63, v65 row_ror:15 row_mask:0xf bank_mask:0xf
	s_and_saveexec_b64 s[64:65], s[80:81]
	s_cbranch_execz .LBB0_671
	v_pk_fma_f32 v[70:71], v[96:97], v[70:71], v[100:101]
	v_pk_fma_f32 v[104:105], v[98:99], v[104:105], v[102:103]
	v_pk_fma_f32 v[70:71], v[44:45], v[92:93], v[70:71]
	v_pk_fma_f32 v[104:105], v[46:47], v[94:95], v[104:105]
	v_pk_fma_f32 v[66:67], v[88:89], v[66:67], v[70:71]
	v_pk_fma_f32 v[68:69], v[90:91], v[68:69], v[104:105]
	v_pk_mul_f32 v[70:71], v[66:67], v[66:67]
	v_pk_fma_f32 v[62:63], v[82:83], v[62:63], v[86:87]
	v_pk_fma_f32 v[60:61], v[80:81], v[60:61], v[84:85]
	v_pk_mul_f32 v[104:105], v[68:69], v[68:69]
	v_pk_fma_f32 v[238:239], v[70:71], s[98:99], s[98:99] op_sel:[0,0,1] op_sel_hi:[1,0,1]
	v_pk_fma_f32 v[240:241], v[104:105], s[98:99], s[98:99] op_sel:[0,0,1] op_sel_hi:[1,0,1]
	v_pk_mul_f32 v[238:239], v[66:67], v[238:239]
	v_pk_mul_f32 v[240:241], v[68:69], v[240:241]
	v_pk_mul_f32 v[238:239], v[238:239], s[100:101] op_sel_hi:[1,0]
	v_pk_mul_f32 v[240:241], v[240:241], s[100:101] op_sel_hi:[1,0]
	v_exp_f32_e32 v238, v238
	v_exp_f32_e32 v240, v240
	v_exp_f32_e32 v239, v239
	v_exp_f32_e32 v241, v241
	v_pk_fma_f32 v[60:61], v[40:41], v[76:77], v[60:61]
	v_pk_add_f32 v[238:239], v[238:239], s[98:99] op_sel:[0,1] op_sel_hi:[1,1]
	v_pk_add_f32 v[240:241], v[240:241], s[98:99] op_sel:[0,1] op_sel_hi:[1,1]
	v_pk_fma_f32 v[62:63], v[42:43], v[78:79], v[62:63]
	v_rcp_f32_e32 v70, v238
	v_pk_fma_f32 v[56:57], v[72:73], v[56:57], v[60:61]
	v_pk_fma_f32 v[58:59], v[74:75], v[58:59], v[62:63]
	v_pk_mul_f32 v[60:61], v[56:57], v[56:57]
	v_pk_mul_f32 v[62:63], v[58:59], v[58:59]
	v_pk_fma_f32 v[242:243], v[60:61], s[98:99], s[98:99] op_sel:[0,0,1] op_sel_hi:[1,0,1]
	v_pk_fma_f32 v[244:245], v[62:63], s[98:99], s[98:99] op_sel:[0,0,1] op_sel_hi:[1,0,1]
	v_pk_mul_f32 v[242:243], v[56:57], v[242:243]
	v_pk_mul_f32 v[244:245], v[58:59], v[244:245]
	v_pk_mul_f32 v[242:243], v[242:243], s[100:101] op_sel_hi:[1,0]
	v_pk_mul_f32 v[244:245], v[244:245], s[100:101] op_sel_hi:[1,0]
	v_exp_f32_e32 v242, v242
	v_exp_f32_e32 v244, v244
	v_exp_f32_e32 v243, v243
	v_exp_f32_e32 v245, v245
	v_rcp_f32_e32 v104, v240
	v_rcp_f32_e32 v105, v241
	v_rcp_f32_e32 v71, v239
	v_pk_add_f32 v[242:243], v[242:243], s[98:99] op_sel:[0,1] op_sel_hi:[1,1]
	v_pk_add_f32 v[244:245], v[244:245], s[98:99] op_sel:[0,1] op_sel_hi:[1,1]
	v_rcp_f32_e32 v60, v242
	v_rcp_f32_e32 v62, v244
	v_rcp_f32_e32 v63, v245
	v_rcp_f32_e32 v61, v243
	v_pk_mul_f32 v[66:67], v[66:67], v[70:71]
	v_ashrrev_i32_e32 v65, 31, v64
	v_pk_mul_f32 v[52:53], v[52:53], v[66:67]
	v_pk_mul_f32 v[58:59], v[58:59], v[62:63]
	v_pk_mul_f32 v[56:57], v[56:57], v[60:61]
	v_pk_mul_f32 v[58:59], v[50:51], v[58:59]
	v_pk_mul_f32 v[50:51], v[48:49], v[56:57]
	v_cvt_pk_bf16_f32 v48, v52, v53
	v_lshlrev_b64 v[52:53], 13, v[64:65]
	v_lshl_add_u64 v[52:53], s[44:45], 0, v[52:53]
	v_pk_mul_f32 v[68:69], v[68:69], v[104:105]
	v_lshl_add_u64 v[52:53], v[176:177], 1, v[52:53]
	v_pk_mul_f32 v[54:55], v[54:55], v[68:69]
	s_nop 0
	v_cvt_pk_bf16_f32 v49, v54, v55
	v_cvt_pk_bf16_f32 v50, v50, v51
	v_cvt_pk_bf16_f32 v51, v58, v59
	global_store_dwordx4 v[52:53], v[48:51], off nt

; __device__ __forceinline__ unsigned cvt_pk_bf16(float lo, float hi) { unsigned r; asm volatile("v_cvt_pk_bf16_f32 %0, %1, %2" : "=v"(r) : "v"(lo), "v"(hi)); return r; }
; __device__ __forceinline__ float dpp_ror1(float v) { return __builtin_bit_cast(float, __builtin_amdgcn_update_dpp(0, __builtin_bit_cast(int, v), 0x121, 0xf, 0xf, false)); }
; __device__ __forceinline__ float dpp_ror15(float v) { return __builtin_bit_cast(float, __builtin_amdgcn_update_dpp(0, __builtin_bit_cast(int, v), 0x12F, 0xf, 0xf, false)); }
;     __device__ __forceinline__ void operator()(const f32x4 (&acc)[2][2][4][2], const Unit& u, int wr, int wc, int fr, int fq) const {
;     ...
;                 f32x4 res[2];
;                 const float fzp = zp ? 0.f : 1.f, fzn = zn ? 0.f : 1.f;
; #pragma unroll
;                 for (int n = 0; n < 2; ++n) {
;                     const f32x4 g = acc[ai][0][m][n], up = acc[ai][1][m][n];
;                     f32x4 tp = g, tn = g;
;                     if (!fix) { const f32x4 gm = (m > 0) ? acc[ai][0][m - 1][n] : acc[ai ^ 1][0][3][n], gx = (m < 3) ? acc[ai][0][m + 1][n] : acc[ai ^ 1][0][0][n];
;                         tp = (fr == 15) ? gm : g; tn = (fr == 0) ? gx : g; }
;                     f32x4 gp, gn;
; #pragma unroll
;                     for (int j = 0; j < 4; ++j) { gp[j] = dpp_ror1(tp[j]); gn[j] = dpp_ror15(tn[j]); }
;                     const f32x4 cv = (w0[n] * fzp) * gp + (w1[n] * g + ((w2[n] * fzn) * gn + bb[n]));
;                     const f32x4 inner = cv * (cv * cv * 0.044715f + 1.0f) * (-2.0f * 0.7978845608028654f * 1.4426950408889634f);
;                     f32x4 sg;
; #pragma unroll
;                     for (int j = 0; j < 4; ++j) sg[j] = __builtin_amdgcn_rcpf(1.0f + __builtin_amdgcn_exp2f(inner[j]));
;                     res[n] = cv * sg * up;
;                 }
;                 if (valid) { u32x4 w; w.x = cvt_pk_bf16(res[0][0], res[0][1]); w.y = cvt_pk_bf16(res[0][2], res[0][3]); w.z = cvt_pk_bf16(res[1][0], res[1][1]); w.w = cvt_pk_bf16(res[1][2], res[1][3]);
;                     __builtin_nontemporal_store(w, (u32x4*)(ACT + (size_t)grow * 4096 + ch0)); }
.LBB0_677:
	v_cndmask_b32_e64 v53, v22, v14, s[18:19]
	v_cndmask_b32_e64 v47, v23, v47, s[16:17]
	v_cndmask_b32_e64 v51, v20, v12, s[18:19]
	v_mov_b32_dpp v56, v53 row_ror:15 row_mask:0xf bank_mask:0xf
	v_cndmask_b32_e64 v45, v21, v45, s[16:17]
	v_mov_b32_dpp v53, v47 row_ror:1 row_mask:0xf bank_mask:0xf
	v_cndmask_b32_e64 v47, v19, v43, s[16:17]
	v_cndmask_b32_e64 v43, v18, v42, s[16:17]
	v_cndmask_b32_e64 v42, v17, v41, s[16:17]
	v_cndmask_b32_e64 v41, v16, v40, s[16:17]
	v_cndmask_b32_e64 v44, v20, v44, s[16:17]
	v_cndmask_b32_e64 v52, v21, v13, s[18:19]
	v_mov_b32_dpp v54, v51 row_ror:15 row_mask:0xf bank_mask:0xf
	v_mov_b32_dpp v40, v41 row_ror:1 row_mask:0xf bank_mask:0xf
	v_cndmask_b32_e64 v46, v22, v46, s[16:17]
	v_mov_b32_dpp v50, v44 row_ror:1 row_mask:0xf bank_mask:0xf
	v_mov_b32_dpp v51, v45 row_ror:1 row_mask:0xf bank_mask:0xf
	v_mov_b32_dpp v55, v52 row_ror:15 row_mask:0xf bank_mask:0xf
	v_cndmask_b32_e64 v45, v16, v8, s[18:19]
	v_mov_b32_dpp v41, v42 row_ror:1 row_mask:0xf bank_mask:0xf
	v_cndmask_b32_e64 v49, v23, v15, s[18:19]
	v_mov_b32_dpp v52, v46 row_ror:1 row_mask:0xf bank_mask:0xf
	v_cndmask_b32_e64 v46, v17, v9, s[18:19]
	v_mov_b32_dpp v44, v45 row_ror:15 row_mask:0xf bank_mask:0xf
	v_mov_b32_dpp v42, v43 row_ror:1 row_mask:0xf bank_mask:0xf
	v_mov_b32_dpp v57, v49 row_ror:15 row_mask:0xf bank_mask:0xf
	v_cndmask_b32_e64 v49, v19, v11, s[18:19]
	v_cndmask_b32_e64 v58, v18, v10, s[18:19]
	v_mov_b32_dpp v45, v46 row_ror:15 row_mask:0xf bank_mask:0xf
	v_mov_b32_dpp v43, v47 row_ror:1 row_mask:0xf bank_mask:0xf
	v_mov_b32_dpp v46, v58 row_ror:15 row_mask:0xf bank_mask:0xf
	s_nop 0
	v_mov_b32_dpp v47, v49 row_ror:15 row_mask:0xf bank_mask:0xf
	s_and_saveexec_b64 s[64:65], s[80:81]
	s_cbranch_execz .LBB0_679
	v_pk_fma_f32 v[54:55], v[96:97], v[54:55], v[100:101]
	v_pk_fma_f32 v[56:57], v[98:99], v[56:57], v[102:103]
	v_pk_fma_f32 v[54:55], v[20:21], v[92:93], v[54:55]
	v_pk_fma_f32 v[56:57], v[22:23], v[94:95], v[56:57]
	v_pk_fma_f32 v[50:51], v[88:89], v[50:51], v[54:55]
	v_pk_fma_f32 v[52:53], v[90:91], v[52:53], v[56:57]
	v_pk_mul_f32 v[54:55], v[50:51], v[50:51]
	v_pk_fma_f32 v[46:47], v[82:83], v[46:47], v[86:87]
	v_pk_fma_f32 v[44:45], v[80:81], v[44:45], v[84:85]
	v_pk_mul_f32 v[56:57], v[52:53], v[52:53]
	v_pk_fma_f32 v[238:239], v[54:55], s[98:99], s[98:99] op_sel:[0,0,1] op_sel_hi:[1,0,1]
	v_pk_fma_f32 v[240:241], v[56:57], s[98:99], s[98:99] op_sel:[0,0,1] op_sel_hi:[1,0,1]
	v_pk_mul_f32 v[238:239], v[50:51], v[238:239]
	v_pk_mul_f32 v[240:241], v[52:53], v[240:241]
	v_pk_mul_f32 v[238:239], v[238:239], s[100:101] op_sel_hi:[1,0]
	v_pk_mul_f32 v[240:241], v[240:241], s[100:101] op_sel_hi:[1,0]
	v_exp_f32_e32 v238, v238
	v_exp_f32_e32 v240, v240
	v_exp_f32_e32 v239, v239
	v_exp_f32_e32 v241, v241
	v_pk_fma_f32 v[44:45], v[16:17], v[76:77], v[44:45]
	v_pk_add_f32 v[238:239], v[238:239], s[98:99] op_sel:[0,1] op_sel_hi:[1,1]
	v_pk_add_f32 v[240:241], v[240:241], s[98:99] op_sel:[0,1] op_sel_hi:[1,1]
	v_pk_fma_f32 v[46:47], v[18:19], v[78:79], v[46:47]
	v_rcp_f32_e32 v54, v238
	v_pk_fma_f32 v[40:41], v[72:73], v[40:41], v[44:45]
	v_pk_fma_f32 v[42:43], v[74:75], v[42:43], v[46:47]
	v_pk_mul_f32 v[44:45], v[40:41], v[40:41]
	v_pk_mul_f32 v[46:47], v[42:43], v[42:43]
	v_pk_fma_f32 v[242:243], v[44:45], s[98:99], s[98:99] op_sel:[0,0,1] op_sel_hi:[1,0,1]
	v_pk_fma_f32 v[244:245], v[46:47], s[98:99], s[98:99] op_sel:[0,0,1] op_sel_hi:[1,0,1]
	v_pk_mul_f32 v[242:243], v[40:41], v[242:243]
	v_pk_mul_f32 v[244:245], v[42:43], v[244:245]
	v_pk_mul_f32 v[242:243], v[242:243], s[100:101] op_sel_hi:[1,0]
	v_pk_mul_f32 v[244:245], v[244:245], s[100:101] op_sel_hi:[1,0]
	v_exp_f32_e32 v242, v242
	v_exp_f32_e32 v244, v244
	v_exp_f32_e32 v243, v243
	v_exp_f32_e32 v245, v245
	v_rcp_f32_e32 v56, v240
	v_rcp_f32_e32 v57, v241
	v_rcp_f32_e32 v55, v239
	v_pk_add_f32 v[242:243], v[242:243], s[98:99] op_sel:[0,1] op_sel_hi:[1,1]
	v_pk_add_f32 v[244:245], v[244:245], s[98:99] op_sel:[0,1] op_sel_hi:[1,1]
	v_rcp_f32_e32 v44, v242
	v_rcp_f32_e32 v46, v244
	v_rcp_f32_e32 v47, v245
	v_rcp_f32_e32 v45, v243
	v_pk_mul_f32 v[50:51], v[50:51], v[54:55]
	v_ashrrev_i32_e32 v49, 31, v48
	v_pk_mul_f32 v[32:33], v[32:33], v[50:51]
	v_pk_mul_f32 v[42:43], v[42:43], v[46:47]
	v_pk_mul_f32 v[40:41], v[40:41], v[44:45]
	v_pk_mul_f32 v[42:43], v[26:27], v[42:43]
	v_pk_mul_f32 v[26:27], v[24:25], v[40:41]
	v_cvt_pk_bf16_f32 v24, v32, v33
	v_lshlrev_b64 v[32:33], 13, v[48:49]
	v_lshl_add_u64 v[32:33], s[44:45], 0, v[32:33]
	v_pk_mul_f32 v[52:53], v[52:53], v[56:57]
	v_lshl_add_u64 v[32:33], v[176:177], 1, v[32:33]
	v_pk_mul_f32 v[34:35], v[34:35], v[52:53]
	s_nop 0
	v_cvt_pk_bf16_f32 v25, v34, v35
	v_cvt_pk_bf16_f32 v26, v26, v27
	v_cvt_pk_bf16_f32 v27, v42, v43
	global_store_dwordx4 v[32:33], v[24:27], off nt

; __device__ __forceinline__ unsigned cvt_pk_bf16(float lo, float hi) { unsigned r; asm volatile("v_cvt_pk_bf16_f32 %0, %1, %2" : "=v"(r) : "v"(lo), "v"(hi)); return r; }
; __device__ __forceinline__ float dpp_ror1(float v) { return __builtin_bit_cast(float, __builtin_amdgcn_update_dpp(0, __builtin_bit_cast(int, v), 0x121, 0xf, 0xf, false)); }
; __device__ __forceinline__ float dpp_ror15(float v) { return __builtin_bit_cast(float, __builtin_amdgcn_update_dpp(0, __builtin_bit_cast(int, v), 0x12F, 0xf, 0xf, false)); }
;     __device__ __forceinline__ void operator()(const f32x4 (&acc)[2][2][4][2], const Unit& u, int wr, int wc, int fr, int fq) const {
;     ...
;                 f32x4 res[2];
;                 const float fzp = zp ? 0.f : 1.f, fzn = zn ? 0.f : 1.f;
; #pragma unroll
;                 for (int n = 0; n < 2; ++n) {
;                     const f32x4 g = acc[ai][0][m][n], up = acc[ai][1][m][n];
;                     f32x4 tp = g, tn = g;
;                     if (!fix) { const f32x4 gm = (m > 0) ? acc[ai][0][m - 1][n] : acc[ai ^ 1][0][3][n], gx = (m < 3) ? acc[ai][0][m + 1][n] : acc[ai ^ 1][0][0][n];
;                         tp = (fr == 15) ? gm : g; tn = (fr == 0) ? gx : g; }
;                     f32x4 gp, gn;
; #pragma unroll
;                     for (int j = 0; j < 4; ++j) { gp[j] = dpp_ror1(tp[j]); gn[j] = dpp_ror15(tn[j]); }
;                     const f32x4 cv = (w0[n] * fzp) * gp + (w1[n] * g + ((w2[n] * fzn) * gn + bb[n]));
;                     const f32x4 inner = cv * (cv * cv * 0.044715f + 1.0f) * (-2.0f * 0.7978845608028654f * 1.4426950408889634f);
;                     f32x4 sg;
; #pragma unroll
;                     for (int j = 0; j < 4; ++j) sg[j] = __builtin_amdgcn_rcpf(1.0f + __builtin_amdgcn_exp2f(inner[j]));
;                     res[n] = cv * sg * up;
;                 }
;                 if (valid) { u32x4 w; w.x = cvt_pk_bf16(res[0][0], res[0][1]); w.y = cvt_pk_bf16(res[0][2], res[0][3]); w.z = cvt_pk_bf16(res[1][0], res[1][1]); w.w = cvt_pk_bf16(res[1][2], res[1][3]);
;                     __builtin_nontemporal_store(w, (u32x4*)(ACT + (size_t)grow * 4096 + ch0)); }
.LBB0_685:
	v_cndmask_b32_e64 v33, v14, v38, s[18:19]
	v_cndmask_b32_e64 v27, v12, v36, s[18:19]
	v_cndmask_b32_e64 v23, v15, v23, s[16:17]
	v_mov_b32_dpp v36, v33 row_ror:15 row_mask:0xf bank_mask:0xf
	v_cndmask_b32_e64 v21, v13, v21, s[16:17]
	v_cndmask_b32_e64 v20, v12, v20, s[16:17]
	v_mov_b32_dpp v33, v23 row_ror:1 row_mask:0xf bank_mask:0xf
	v_cndmask_b32_e64 v23, v11, v19, s[16:17]
	v_cndmask_b32_e64 v19, v10, v18, s[16:17]
	v_cndmask_b32_e64 v18, v9, v17, s[16:17]
	v_cndmask_b32_e64 v17, v8, v16, s[16:17]
	v_cndmask_b32_e64 v32, v13, v37, s[18:19]
	v_mov_b32_dpp v34, v27 row_ror:15 row_mask:0xf bank_mask:0xf
	v_mov_b32_dpp v16, v17 row_ror:1 row_mask:0xf bank_mask:0xf
	v_cndmask_b32_e64 v22, v14, v22, s[16:17]
	v_mov_b32_dpp v26, v20 row_ror:1 row_mask:0xf bank_mask:0xf
	v_mov_b32_dpp v27, v21 row_ror:1 row_mask:0xf bank_mask:0xf
	v_mov_b32_dpp v35, v32 row_ror:15 row_mask:0xf bank_mask:0xf
	v_cndmask_b32_e64 v21, v8, v28, s[18:19]
	v_mov_b32_dpp v17, v18 row_ror:1 row_mask:0xf bank_mask:0xf
	v_cndmask_b32_e64 v25, v15, v39, s[18:19]
	v_mov_b32_dpp v32, v22 row_ror:1 row_mask:0xf bank_mask:0xf
	v_cndmask_b32_e64 v22, v9, v29, s[18:19]
	v_mov_b32_dpp v20, v21 row_ror:15 row_mask:0xf bank_mask:0xf
	v_mov_b32_dpp v18, v19 row_ror:1 row_mask:0xf bank_mask:0xf
	v_mov_b32_dpp v37, v25 row_ror:15 row_mask:0xf bank_mask:0xf
	v_cndmask_b32_e64 v25, v11, v31, s[18:19]
	v_cndmask_b32_e64 v30, v10, v30, s[18:19]
	v_mov_b32_dpp v21, v22 row_ror:15 row_mask:0xf bank_mask:0xf
	v_mov_b32_dpp v19, v23 row_ror:1 row_mask:0xf bank_mask:0xf
	v_mov_b32_dpp v22, v30 row_ror:15 row_mask:0xf bank_mask:0xf
	s_nop 0
	v_mov_b32_dpp v23, v25 row_ror:15 row_mask:0xf bank_mask:0xf
	s_and_saveexec_b64 s[16:17], s[20:21]
	s_cbranch_execz .LBB0_687
	v_pk_fma_f32 v[30:31], v[96:97], v[34:35], v[100:101]
	v_pk_fma_f32 v[28:29], v[98:99], v[36:37], v[102:103]
	v_pk_fma_f32 v[12:13], v[12:13], v[92:93], v[30:31]
	v_pk_fma_f32 v[14:15], v[14:15], v[94:95], v[28:29]
	v_pk_fma_f32 v[12:13], v[88:89], v[26:27], v[12:13]
	v_pk_fma_f32 v[14:15], v[90:91], v[32:33], v[14:15]
	v_pk_mul_f32 v[26:27], v[12:13], v[12:13]
	v_pk_fma_f32 v[22:23], v[82:83], v[22:23], v[86:87]
	v_pk_fma_f32 v[20:21], v[80:81], v[20:21], v[84:85]
	v_pk_mul_f32 v[28:29], v[14:15], v[14:15]
	v_pk_fma_f32 v[238:239], v[26:27], s[98:99], s[98:99] op_sel:[0,0,1] op_sel_hi:[1,0,1]
	v_pk_fma_f32 v[240:241], v[28:29], s[98:99], s[98:99] op_sel:[0,0,1] op_sel_hi:[1,0,1]
	v_pk_mul_f32 v[238:239], v[12:13], v[238:239]
	v_pk_mul_f32 v[240:241], v[14:15], v[240:241]
	v_pk_mul_f32 v[238:239], v[238:239], s[100:101] op_sel_hi:[1,0]
	v_pk_mul_f32 v[240:241], v[240:241], s[100:101] op_sel_hi:[1,0]
	v_exp_f32_e32 v238, v238
	v_exp_f32_e32 v240, v240
	v_exp_f32_e32 v239, v239
	v_exp_f32_e32 v241, v241
	v_pk_fma_f32 v[8:9], v[8:9], v[76:77], v[20:21]
	v_pk_add_f32 v[238:239], v[238:239], s[98:99] op_sel:[0,1] op_sel_hi:[1,1]
	v_pk_add_f32 v[240:241], v[240:241], s[98:99] op_sel:[0,1] op_sel_hi:[1,1]
	v_pk_fma_f32 v[10:11], v[10:11], v[78:79], v[22:23]
	v_rcp_f32_e32 v26, v238
	v_pk_fma_f32 v[8:9], v[72:73], v[16:17], v[8:9]
	v_pk_fma_f32 v[10:11], v[74:75], v[18:19], v[10:11]
	v_pk_mul_f32 v[16:17], v[8:9], v[8:9]
	v_pk_mul_f32 v[18:19], v[10:11], v[10:11]
	v_pk_fma_f32 v[242:243], v[16:17], s[98:99], s[98:99] op_sel:[0,0,1] op_sel_hi:[1,0,1]
	v_pk_fma_f32 v[244:245], v[18:19], s[98:99], s[98:99] op_sel:[0,0,1] op_sel_hi:[1,0,1]
	v_pk_mul_f32 v[242:243], v[8:9], v[242:243]
	v_pk_mul_f32 v[244:245], v[10:11], v[244:245]
	v_pk_mul_f32 v[242:243], v[242:243], s[100:101] op_sel_hi:[1,0]
	v_pk_mul_f32 v[244:245], v[244:245], s[100:101] op_sel_hi:[1,0]
	v_exp_f32_e32 v242, v242
	v_exp_f32_e32 v244, v244
	v_exp_f32_e32 v243, v243
	v_exp_f32_e32 v245, v245
	v_rcp_f32_e32 v28, v240
	v_rcp_f32_e32 v29, v241
	v_rcp_f32_e32 v27, v239
	v_pk_add_f32 v[242:243], v[242:243], s[98:99] op_sel:[0,1] op_sel_hi:[1,1]
	v_pk_add_f32 v[244:245], v[244:245], s[98:99] op_sel:[0,1] op_sel_hi:[1,1]
	v_rcp_f32_e32 v16, v242
	v_rcp_f32_e32 v18, v244
	v_rcp_f32_e32 v19, v245
	v_rcp_f32_e32 v17, v243
	v_pk_mul_f32 v[12:13], v[12:13], v[26:27]
	v_ashrrev_i32_e32 v25, 31, v24
	v_pk_mul_f32 v[4:5], v[4:5], v[12:13]
	v_pk_mul_f32 v[10:11], v[10:11], v[18:19]
	v_pk_mul_f32 v[8:9], v[8:9], v[16:17]
	v_pk_mul_f32 v[10:11], v[2:3], v[10:11]
	v_pk_mul_f32 v[2:3], v[0:1], v[8:9]
	v_cvt_pk_bf16_f32 v0, v4, v5
	v_lshlrev_b64 v[4:5], 13, v[24:25]
	v_lshl_add_u64 v[4:5], s[44:45], 0, v[4:5]
	v_pk_mul_f32 v[14:15], v[14:15], v[28:29]
	v_lshl_add_u64 v[4:5], v[176:177], 1, v[4:5]
	v_pk_mul_f32 v[6:7], v[6:7], v[14:15]
	s_nop 0
	v_cvt_pk_bf16_f32 v1, v6, v7
	v_cvt_pk_bf16_f32 v2, v2, v3
	v_cvt_pk_bf16_f32 v3, v10, v11
	global_store_dwordx4 v[4:5], v[0:3], off nt
